# mem_attn PV: V^T fragment loads 16 deep rolling instead of 2 in flight, P fragments read once
# speedup vs baseline: 1.0033x; 1.0006x over previous
; __device__ __forceinline__ void mem_attn_phase(int wv, const Args& A, LAS unsigned char* lds, int G) {
;     ...
;     for (int wu = blockIdx.x * 8 + w; wu < (MT / 16) * 4; wu += G * 8) {
;         const int blk = wu >> 3; const int h = blk & 3, tile = (blk >> 2) * 8 + (wu & 7); const size_t row0 = (size_t)tile * 16;
;         const h16* Kb; const h16* VTb;
;         if (row0 < NP) { const int b = (int)(row0 >> 14); Kb = (const h16*)(ws + WS_MK16) + (size_t)b * 256 * 512; VTb = (const h16*)(ws + WS_MVT) + (size_t)(b * 4 + h) * 32768; }
;         else { const int bs = (int)((row0 - NP) >> 6); Kb = (const h16*)(ws + WS_CMK) + (size_t)bs * 256 * 512; VTb = (const h16*)(ws + WS_CMVT) + (size_t)(bs * 4 + h) * 32768; }
;         h16x8 qf[4];
; #pragma unroll
;         for (int ks = 0; ks < 4; ++ks) qf[ks] = __builtin_bit_cast(h16x8, *(const u32x4*)(MQ + (row0 + fr) * 512 + h * 128 + ks * 32 + fq * 8));
;         f32x4 lg[16]; float m = -INFINITY;
; #pragma unroll
;         for (int kt = 0; kt < 16; ++kt) { f32x4 a = {0.f, 0.f, 0.f, 0.f};
; #pragma unroll
;             for (int ks = 0; ks < 4; ++ks) { const h16x8 kf = __builtin_bit_cast(h16x8, *(const u32x4*)(Kb + (size_t)(kt * 16 + fr) * 512 + h * 128 + ks * 32 + fq * 8)); a = __builtin_amdgcn_mfma_f32_16x16x32_f16(kf, qf[ks], a, 0, 0, 0); }
;             lg[kt] = a; m = fmaxf(m, fmaxf(fmaxf(a[0], a[1]), fmaxf(a[2], a[3]))); }
.LBB0_2401:
	s_or_b64 exec, exec, s[26:27]
	v_or_b32_e32 v0, v0, v76
	v_lshlrev_b64 v[88:89], 10, v[0:1]
	v_lshl_add_u64 v[0:1], s[8:9], 0, v[88:89]
	v_lshlrev_b32_e32 v78, 8, v4
	v_lshl_add_u64 v[4:5], v[0:1], 0, v[78:79]
	v_lshl_add_u64 v[0:1], v[2:3], 0, v[78:79]
	v_lshl_add_u64 v[0:1], v[0:1], 0, v[80:81]
	v_lshl_add_u64 v[0:1], v[0:1], 0, v[82:83]
	global_load_dwordx4 v[8:11], v[0:1], off
	v_add_co_u32_e32 v116, vcc, s0, v0
	v_lshl_add_u64 v[2:3], v[4:5], 0, v[80:81]
	s_nop 0
	v_addc_co_u32_e32 v117, vcc, 0, v1, vcc
	v_add_co_u32_e32 v118, vcc, s3, v0
	global_load_dwordx4 v[4:7], v[2:3], off
	s_nop 0
	v_addc_co_u32_e32 v119, vcc, 0, v1, vcc
	global_load_dwordx4 v[12:15], v[116:117], off
	global_load_dwordx4 v[16:19], v[118:119], off
	v_add_co_u32_e32 v120, vcc, s4, v0
	v_add_u32_e32 v77, s52, v77
	s_nop 0
	v_addc_co_u32_e32 v121, vcc, 0, v1, vcc
	v_add_co_u32_e32 v122, vcc, s5, v0
	global_load_dwordx4 v[20:23], v[120:121], off
	s_nop 0
	v_addc_co_u32_e32 v123, vcc, 0, v1, vcc
	v_add_co_u32_e32 v124, vcc, s28, v0
	global_load_dwordx4 v[24:27], v[122:123], off
	s_nop 0
	v_addc_co_u32_e32 v125, vcc, 0, v1, vcc
	global_load_dwordx4 v[28:31], v[124:125], off
	global_load_dwordx4 v[32:35], v[0:1], off offset:64
	global_load_dwordx4 v[52:55], v[2:3], off offset:64
	global_load_dwordx4 v[36:39], v[116:117], off offset:64
	global_load_dwordx4 v[40:43], v[118:119], off offset:64
	global_load_dwordx4 v[44:47], v[120:121], off offset:64
	global_load_dwordx4 v[48:51], v[122:123], off offset:64
	global_load_dwordx4 v[60:63], v[124:125], off offset:64
	global_load_dwordx4 v[68:71], v[0:1], off offset:128
	global_load_dwordx4 v[56:59], v[2:3], off offset:128
	global_load_dwordx4 v[72:75], v[116:117], off offset:128
	global_load_dwordx4 v[96:99], v[118:119], off offset:128
	global_load_dwordx4 v[100:103], v[120:121], off offset:128
	global_load_dwordx4 v[104:107], v[122:123], off offset:128
	global_load_dwordx4 v[108:111], v[124:125], off offset:128
	global_load_dwordx4 v[112:115], v[0:1], off offset:192
	global_load_dwordx4 v[64:67], v[2:3], off offset:192
	v_add_co_u32_e32 v2, vcc, s29, v0
	s_waitcnt vmcnt(16)
	v_mfma_f32_16x16x32_f16 v[28:31], v[28:31], v[4:7], 0
	v_addc_co_u32_e32 v3, vcc, 0, v1, vcc
	v_mfma_f32_16x16x32_f16 v[8:11], v[8:11], v[4:7], 0
	v_mfma_f32_16x16x32_f16 v[16:19], v[16:19], v[4:7], 0
	s_waitcnt vmcnt(14)
	v_mfma_f32_16x16x32_f16 v[8:11], v[32:35], v[52:55], v[8:11]
	global_load_dwordx4 v[32:35], v[116:117], off offset:192
	v_mfma_f32_16x16x32_f16 v[12:15], v[12:15], v[4:7], 0
	s_waitcnt vmcnt(13)
	v_mfma_f32_16x16x32_f16 v[16:19], v[40:43], v[52:55], v[16:19]
	global_load_dwordx4 v[40:43], v[120:121], off offset:192
	v_mfma_f32_16x16x32_f16 v[12:15], v[36:39], v[52:55], v[12:15]
	global_load_dwordx4 v[36:39], v[118:119], off offset:192
	v_mfma_f32_16x16x32_f16 v[20:23], v[20:23], v[4:7], 0
	s_waitcnt vmcnt(14)
	v_mfma_f32_16x16x32_f16 v[20:23], v[44:47], v[52:55], v[20:23]
	global_load_dwordx4 v[44:47], v[122:123], off offset:192
	global_load_dwordx4 v[116:119], v[124:125], off offset:192
	s_nop 0
	global_load_dwordx4 v[120:123], v[2:3], off
	global_load_dwordx4 v[124:127], v[2:3], off offset:64
	global_load_dwordx4 v[128:131], v[2:3], off offset:128
	global_load_dwordx4 v[132:135], v[2:3], off offset:192
	v_add_co_u32_e32 v2, vcc, s30, v0
	v_mfma_f32_16x16x32_f16 v[24:27], v[24:27], v[4:7], 0
	s_nop 0
	v_addc_co_u32_e32 v3, vcc, 0, v1, vcc
	s_waitcnt vmcnt(14)
	v_mfma_f32_16x16x32_f16 v[16:19], v[96:99], v[56:59], v[16:19]
	global_load_dwordx4 v[96:99], v[2:3], off
	v_mfma_f32_16x16x32_f16 v[24:27], v[48:51], v[52:55], v[24:27]
	s_waitcnt vmcnt(14)
	v_mfma_f32_16x16x32_f16 v[20:23], v[100:103], v[56:59], v[20:23]
	global_load_dwordx4 v[100:103], v[2:3], off offset:64
	s_waitcnt vmcnt(14)
	v_mfma_f32_16x16x32_f16 v[24:27], v[104:107], v[56:59], v[24:27]
	global_load_dwordx4 v[104:107], v[2:3], off offset:128
	v_mfma_f32_16x16x32_f16 v[8:11], v[68:71], v[56:59], v[8:11]
	v_mfma_f32_16x16x32_f16 v[12:15], v[72:75], v[56:59], v[12:15]
	s_waitcnt vmcnt(12)
	v_mfma_f32_16x16x32_f16 v[72:75], v[112:115], v[64:67], v[8:11]
	s_nop 4
	global_load_dwordx4 v[8:11], v[2:3], off offset:192
	v_add_co_u32_e32 v2, vcc, s31, v0
	s_waitcnt vmcnt(12)
	v_mfma_f32_16x16x32_f16 v[68:71], v[32:35], v[64:67], v[12:15]
	v_addc_co_u32_e32 v3, vcc, 0, v1, vcc
	global_load_dwordx4 v[32:35], v[2:3], off
	v_mfma_f32_16x16x32_f16 v[28:31], v[60:63], v[52:55], v[28:31]
	s_waitcnt vmcnt(12)
	v_mfma_f32_16x16x32_f16 v[48:51], v[40:43], v[64:67], v[20:23]
	global_load_dwordx4 v[40:43], v[2:3], off offset:64
	v_mfma_f32_16x16x32_f16 v[28:31], v[108:111], v[56:59], v[28:31]
	s_waitcnt vmcnt(12)
	v_mfma_f32_16x16x32_f16 v[60:63], v[36:39], v[64:67], v[16:19]
	s_waitcnt vmcnt(11)
	v_mfma_f32_16x16x32_f16 v[36:39], v[44:47], v[64:67], v[24:27]
	s_nop 2
	global_load_dwordx4 v[24:27], v[2:3], off offset:128
	s_waitcnt vmcnt(11)
	v_mfma_f32_16x16x32_f16 v[20:23], v[116:119], v[64:67], v[28:31]
	s_nop 2
	global_load_dwordx4 v[28:31], v[2:3], off offset:192
	v_add_co_u32_e32 v2, vcc, s33, v0
	s_waitcnt vmcnt(11)
	v_mfma_f32_16x16x32_f16 v[12:15], v[120:123], v[4:7], 0
	v_addc_co_u32_e32 v3, vcc, 0, v1, vcc
	global_load_dwordx4 v[44:47], v[2:3], off
	global_load_dwordx4 v[108:111], v[2:3], off offset:64
	global_load_dwordx4 v[112:115], v[2:3], off offset:128
	global_load_dwordx4 v[116:119], v[2:3], off offset:192
	s_waitcnt vmcnt(14)
	v_mfma_f32_16x16x32_f16 v[12:15], v[124:127], v[52:55], v[12:15]
	v_add_co_u32_e32 v2, vcc, s34, v0
	s_waitcnt vmcnt(13)
	v_mfma_f32_16x16x32_f16 v[12:15], v[128:131], v[56:59], v[12:15]
	v_addc_co_u32_e32 v3, vcc, 0, v1, vcc
	s_waitcnt vmcnt(12)
; __device__ __forceinline__ void mem_attn_phase(int wv, const Args& A, LAS unsigned char* lds, int G) {
;     ...
;         for (int kt = 0; kt < 16; ++kt) { f32x4 a = {0.f, 0.f, 0.f, 0.f};
; #pragma unroll
;             for (int ks = 0; ks < 4; ++ks) { const h16x8 kf = __builtin_bit_cast(h16x8, *(const u32x4*)(Kb + (size_t)(kt * 16 + fr) * 512 + h * 128 + ks * 32 + fq * 8)); a = __builtin_amdgcn_mfma_f32_16x16x32_f16(kf, qf[ks], a, 0, 0, 0); }
;             lg[kt] = a; m = fmaxf(m, fmaxf(fmaxf(a[0], a[1]), fmaxf(a[2], a[3]))); }
;         m = fmaxf(m, __shfl_xor(m, 16)); m = fmaxf(m, __shfl_xor(m, 32));
	v_mfma_f32_16x16x32_f16 v[16:19], v[132:135], v[64:67], v[12:15]
	s_waitcnt vmcnt(11)
	v_mfma_f32_16x16x32_f16 v[12:15], v[96:99], v[4:7], 0
	global_load_dwordx4 v[96:99], v[2:3], off
	s_waitcnt vmcnt(11)
	v_mfma_f32_16x16x32_f16 v[12:15], v[100:103], v[52:55], v[12:15]
	global_load_dwordx4 v[100:103], v[2:3], off offset:64
	s_waitcnt vmcnt(11)
	v_mfma_f32_16x16x32_f16 v[12:15], v[104:107], v[56:59], v[12:15]
	global_load_dwordx4 v[104:107], v[2:3], off offset:128
	s_waitcnt vmcnt(11)
	v_mfma_f32_16x16x32_f16 v[12:15], v[8:11], v[64:67], v[12:15]
	global_load_dwordx4 v[8:11], v[2:3], off offset:192
	v_add_co_u32_e32 v2, vcc, s35, v0
	s_waitcnt vmcnt(11)
	v_mfma_f32_16x16x32_f16 v[32:35], v[32:35], v[4:7], 0
	v_addc_co_u32_e32 v3, vcc, 0, v1, vcc
	global_load_dwordx4 v[120:123], v[2:3], off
	global_load_dwordx4 v[124:127], v[2:3], off offset:64
	global_load_dwordx4 v[128:131], v[2:3], off offset:128
	global_load_dwordx4 v[132:135], v[2:3], off offset:192
	v_add_co_u32_e32 v2, vcc, s36, v0
	s_waitcnt vmcnt(14)
	v_mfma_f32_16x16x32_f16 v[32:35], v[40:43], v[52:55], v[32:35]
	v_addc_co_u32_e32 v3, vcc, 0, v1, vcc
	global_load_dwordx4 v[136:139], v[2:3], off
	s_waitcnt vmcnt(14)
	v_mfma_f32_16x16x32_f16 v[24:27], v[24:27], v[56:59], v[32:35]
	global_load_dwordx4 v[140:143], v[2:3], off offset:64
	global_load_dwordx4 v[144:147], v[2:3], off offset:128
	s_waitcnt vmcnt(15)
	v_mfma_f32_16x16x32_f16 v[24:27], v[28:31], v[64:67], v[24:27]
	global_load_dwordx4 v[28:31], v[2:3], off offset:192
	v_add_co_u32_e32 v2, vcc, s37, v0
	s_waitcnt vmcnt(15)
	v_mfma_f32_16x16x32_f16 v[32:35], v[44:47], v[4:7], 0
	v_addc_co_u32_e32 v3, vcc, 0, v1, vcc
	global_load_dwordx4 v[148:151], v[2:3], off
	s_waitcnt vmcnt(15)
	v_mfma_f32_16x16x32_f16 v[32:35], v[108:111], v[52:55], v[32:35]
	global_load_dwordx4 v[152:155], v[2:3], off offset:64
	global_load_dwordx4 v[156:159], v[2:3], off offset:128
	global_load_dwordx4 v[108:111], v[2:3], off offset:192
	v_add_co_u32_e32 v2, vcc, s38, v0
	s_waitcnt vmcnt(17)
	v_mfma_f32_16x16x32_f16 v[32:35], v[112:115], v[56:59], v[32:35]
	v_addc_co_u32_e32 v3, vcc, 0, v1, vcc
	global_load_dwordx4 v[160:163], v[2:3], off
	s_waitcnt vmcnt(17)
	v_mfma_f32_16x16x32_f16 v[40:43], v[116:119], v[64:67], v[32:35]
	global_load_dwordx4 v[112:115], v[2:3], off offset:64
	global_load_dwordx4 v[164:167], v[2:3], off offset:128
	global_load_dwordx4 v[116:119], v[2:3], off offset:192
	s_nop 0
	v_add_co_u32_e32 v32, vcc, s39, v0
	v_max_f32_e32 v34, v75, v75
	s_nop 0
	v_addc_co_u32_e32 v33, vcc, 0, v1, vcc
	global_load_dwordx4 v[178:181], v[32:33], off
	s_waitcnt vmcnt(20)
	v_mfma_f32_16x16x32_f16 v[0:3], v[96:99], v[4:7], 0
	global_load_dwordx4 v[96:99], v[32:33], off offset:64
	v_max_f32_e32 v35, v74, v74
	v_max_f32_e32 v34, v35, v34
	s_waitcnt vmcnt(20)
	v_mfma_f32_16x16x32_f16 v[0:3], v[100:103], v[52:55], v[0:3]
	global_load_dwordx4 v[100:103], v[32:33], off offset:128
	v_max3_f32 v34, v72, v73, v34
	s_waitcnt vmcnt(20)
	v_mfma_f32_16x16x32_f16 v[0:3], v[104:107], v[56:59], v[0:3]
	global_load_dwordx4 v[104:107], v[32:33], off offset:192
	v_max_f32_e32 v32, v71, v71
	v_max_f32_e32 v33, v70, v70
	v_max_f32_e32 v32, v33, v32
	s_waitcnt vmcnt(20)
	v_mfma_f32_16x16x32_f16 v[44:47], v[8:11], v[64:67], v[0:3]
	v_max_f32_e32 v9, v63, v63
	v_max_f32_e32 v10, v62, v62
	v_max_f32_e32 v9, v10, v9
	v_max3_f32 v0, v68, v69, v32
	v_max3_f32 v8, v34, s1, v0
	s_waitcnt vmcnt(19)
	v_mfma_f32_16x16x32_f16 v[0:3], v[120:123], v[4:7], 0
	v_max_f32_e32 v10, v51, v51
	v_max_f32_e32 v11, v50, v50
	v_max_f32_e32 v10, v11, v10
	s_waitcnt vmcnt(18)
	v_mfma_f32_16x16x32_f16 v[0:3], v[124:127], v[52:55], v[0:3]
	v_max3_f32 v9, v60, v61, v9
	v_max3_f32 v10, v48, v49, v10
	v_max3_f32 v8, v8, v9, v10
	s_waitcnt vmcnt(17)
	v_mfma_f32_16x16x32_f16 v[0:3], v[128:131], v[56:59], v[0:3]
	v_max_f32_e32 v9, v39, v39
	v_max_f32_e32 v10, v23, v23
	v_max_f32_e32 v11, v22, v22
	s_waitcnt vmcnt(16)
	v_mfma_f32_16x16x32_f16 v[32:35], v[132:135], v[64:67], v[0:3]
	v_max_f32_e32 v10, v11, v10
	v_max3_f32 v10, v20, v21, v10
	s_nop 0
	v_max_f32_e32 v0, v38, v38
	v_max_f32_e32 v0, v0, v9
	v_max3_f32 v9, v36, v37, v0
	s_waitcnt vmcnt(15)
	v_mfma_f32_16x16x32_f16 v[0:3], v[136:139], v[4:7], 0
	v_max3_f32 v8, v8, v9, v10
	v_max_f32_e32 v9, v19, v19
	v_max_f32_e32 v10, v18, v18
	s_waitcnt vmcnt(14)
	v_mfma_f32_16x16x32_f16 v[0:3], v[140:143], v[52:55], v[0:3]
	v_max_f32_e32 v9, v10, v9
	v_max3_f32 v9, v16, v17, v9
	s_waitcnt vmcnt(13)
	v_mfma_f32_16x16x32_f16 v[0:3], v[144:147], v[56:59], v[0:3]
	s_waitcnt vmcnt(12)
	v_mfma_f32_16x16x32_f16 v[28:31], v[28:31], v[64:67], v[0:3]
	s_nop 5
	v_max_f32_e32 v0, v15, v15
	v_max_f32_e32 v1, v14, v14
	v_max_f32_e32 v10, v1, v0
	s_waitcnt vmcnt(11)
	v_mfma_f32_16x16x32_f16 v[0:3], v[148:151], v[4:7], 0
	v_max3_f32 v10, v12, v13, v10
	v_max3_f32 v95, v8, v9, v10
	v_max_f32_e32 v8, v27, v27
	s_waitcnt vmcnt(10)
	v_mfma_f32_16x16x32_f16 v[0:3], v[152:155], v[52:55], v[0:3]
	v_max_f32_e32 v9, v26, v26
	v_max_f32_e32 v8, v9, v8
	v_max3_f32 v120, v24, v25, v8
	s_waitcnt vmcnt(9)
	v_mfma_f32_16x16x32_f16 v[0:3], v[156:159], v[56:59], v[0:3]
	v_max_f32_e32 v8, v43, v43
	v_max_f32_e32 v9, v42, v42
	v_max_f32_e32 v121, v9, v8
	s_waitcnt vmcnt(8)
	v_mfma_f32_16x16x32_f16 v[8:11], v[108:111], v[64:67], v[0:3]
	v_max_f32_e32 v108, v47, v47
	v_max_f32_e32 v109, v46, v46
	v_max_f32_e32 v108, v109, v108
	v_max3_f32 v0, v40, v41, v121
	v_max3_f32 v95, v95, v120, v0
	s_waitcnt vmcnt(7)
	v_mfma_f32_16x16x32_f16 v[0:3], v[160:163], v[4:7], 0
	v_max_f32_e32 v109, v35, v35
	v_max_f32_e32 v110, v34, v34
	v_max_f32_e32 v109, v110, v109
	s_waitcnt vmcnt(3)
; #define LAS __attribute__((address_space(3)))
; __device__ __forceinline__ void mem_attn_phase(int wv, const Args& A, LAS unsigned char* lds, int G) {
;     ...
;             lg[kt] = a; m = fmaxf(m, fmaxf(fmaxf(a[0], a[1]), fmaxf(a[2], a[3]))); }
;         m = fmaxf(m, __shfl_xor(m, 16)); m = fmaxf(m, __shfl_xor(m, 32));
;         float sm = 0.f;
; #pragma unroll
;         for (int kt = 0; kt < 16; ++kt) { h16x4 p4;
; #pragma unroll
;             for (int r = 0; r < 4; ++r) { const float p = __expf(lg[kt][r] - m); sm += p; p4[r] = (h16)p; }
;             *(LAS u32x2*)(Pw + fr * 264 + kt * 16 + fq * 4) = __builtin_bit_cast(u32x2, p4); }
;         sm += __shfl_xor(sm, 16); sm += __shfl_xor(sm, 32);
	v_mfma_f32_16x16x32_f16 v[4:7], v[178:181], v[4:7], 0
	v_max3_f32 v108, v44, v45, v108
	v_max3_f32 v109, v32, v33, v109
	v_max3_f32 v95, v95, v108, v109
	v_mfma_f32_16x16x32_f16 v[0:3], v[112:115], v[52:55], v[0:3]
	v_max_f32_e32 v108, v31, v31
	v_max_f32_e32 v109, v30, v30
	v_max_f32_e32 v108, v109, v108
	s_waitcnt vmcnt(2)
	v_mfma_f32_16x16x32_f16 v[4:7], v[96:99], v[52:55], v[4:7]
	v_max_f32_e32 v109, v11, v11
	v_max_f32_e32 v110, v10, v10
	v_max_f32_e32 v109, v110, v109
	v_mfma_f32_16x16x32_f16 v[0:3], v[164:167], v[56:59], v[0:3]
	v_max3_f32 v108, v28, v29, v108
	v_max3_f32 v52, v8, v9, v109
	v_max3_f32 v52, v95, v108, v52
	s_waitcnt vmcnt(1)
	v_mfma_f32_16x16x32_f16 v[4:7], v[100:103], v[56:59], v[4:7]
	v_mfma_f32_16x16x32_f16 v[0:3], v[116:119], v[64:67], v[0:3]
	s_waitcnt vmcnt(0)
	v_mfma_f32_16x16x32_f16 v[4:7], v[104:107], v[64:67], v[4:7]
	s_nop 5
	v_max_f32_e32 v53, v3, v3
	v_max_f32_e32 v54, v2, v2
	v_max_f32_e32 v53, v54, v53
	v_max_f32_e32 v54, v7, v7
	v_max_f32_e32 v55, v6, v6
	v_max_f32_e32 v54, v55, v54
	v_max3_f32 v53, v0, v1, v53
	v_max3_f32 v54, v4, v5, v54
	v_max3_f32 v52, v52, v53, v54
	ds_bpermute_b32 v53, v175, v52
	s_waitcnt lgkmcnt(0)
	v_max_f32_e32 v53, v53, v53
	v_max_f32_e32 v52, v52, v53
	ds_bpermute_b32 v53, v176, v52
	s_waitcnt lgkmcnt(0)
	v_max_f32_e32 v53, v53, v53
	v_max_f32_e32 v56, v52, v53
	v_sub_f32_e32 v52, v72, v56
	v_sub_f32_e32 v53, v73, v56
	v_mul_f32_e32 v52, 0x3fb8aa3b, v52
	v_mul_f32_e32 v53, 0x3fb8aa3b, v53
	v_exp_f32_e32 v52, v52
	v_exp_f32_e32 v54, v53
	v_sub_f32_e32 v53, v74, v56
	v_mul_f32_e32 v53, 0x3fb8aa3b, v53
	v_sub_f32_e32 v55, v75, v56
	v_exp_f32_e32 v53, v53
	v_mul_f32_e32 v55, 0x3fb8aa3b, v55
	v_exp_f32_e32 v55, v55
	v_add_f32_e32 v57, 0, v52
	v_add_f32_e32 v57, v54, v57
	v_add_f32_e32 v57, v53, v57
	v_add_f32_e32 v57, v55, v57
	v_cvt_pk_f16_f32 v53, v53, v55
	v_cvt_pk_f16_f32 v52, v52, v54
	v_sub_f32_e32 v54, v68, v56
	v_sub_f32_e32 v55, v69, v56
	v_mul_f32_e32 v54, 0x3fb8aa3b, v54
	v_mul_f32_e32 v55, 0x3fb8aa3b, v55
	v_exp_f32_e32 v54, v54
	v_exp_f32_e32 v58, v55
	v_sub_f32_e32 v55, v70, v56
	v_sub_f32_e32 v59, v71, v56
	v_mul_f32_e32 v55, 0x3fb8aa3b, v55
	v_mul_f32_e32 v59, 0x3fb8aa3b, v59
	v_exp_f32_e32 v55, v55
	v_exp_f32_e32 v59, v59
	v_add_f32_e32 v57, v54, v57
	v_add_f32_e32 v57, v58, v57
	v_add_f32_e32 v57, v55, v57
	v_cvt_pk_f16_f32 v55, v55, v59
	v_cvt_pk_f16_f32 v54, v54, v58
	ds_write2_b64 v92, v[52:53], v[54:55] offset1:4
	v_sub_f32_e32 v52, v60, v56
	v_mul_f32_e32 v52, 0x3fb8aa3b, v52
	v_sub_f32_e32 v53, v61, v56
	v_exp_f32_e32 v52, v52
	v_mul_f32_e32 v53, 0x3fb8aa3b, v53
	v_exp_f32_e32 v54, v53
	v_sub_f32_e32 v53, v62, v56
	v_mul_f32_e32 v53, 0x3fb8aa3b, v53
	v_sub_f32_e32 v55, v63, v56
	v_add_f32_e32 v57, v59, v57
	v_exp_f32_e32 v53, v53
	v_mul_f32_e32 v55, 0x3fb8aa3b, v55
	v_sub_f32_e32 v48, v48, v56
	v_sub_f32_e32 v49, v49, v56
	v_exp_f32_e32 v55, v55
	v_add_f32_e32 v57, v52, v57
	v_mul_f32_e32 v48, 0x3fb8aa3b, v48
	v_mul_f32_e32 v49, 0x3fb8aa3b, v49
	v_add_f32_e32 v57, v54, v57
	v_cvt_pk_f16_f32 v52, v52, v54
	v_exp_f32_e32 v48, v48
	v_exp_f32_e32 v54, v49
	v_sub_f32_e32 v49, v50, v56
	v_sub_f32_e32 v50, v51, v56
	v_mul_f32_e32 v49, 0x3fb8aa3b, v49
	v_mul_f32_e32 v50, 0x3fb8aa3b, v50
	v_add_f32_e32 v57, v53, v57
	v_exp_f32_e32 v49, v49
	v_exp_f32_e32 v50, v50
	v_add_f32_e32 v57, v55, v57
	v_add_f32_e32 v51, v48, v57
	v_add_f32_e32 v51, v54, v51
	v_sub_f32_e32 v36, v36, v56
	v_sub_f32_e32 v37, v37, v56
	v_cvt_pk_f16_f32 v53, v53, v55
	v_add_f32_e32 v51, v49, v51
	v_cvt_pk_f16_f32 v49, v49, v50
	v_cvt_pk_f16_f32 v48, v48, v54
	v_mul_f32_e32 v36, 0x3fb8aa3b, v36
	v_mul_f32_e32 v37, 0x3fb8aa3b, v37
	ds_write2_b64 v92, v[52:53], v[48:49] offset0:8 offset1:12
	v_exp_f32_e32 v36, v36
	v_exp_f32_e32 v48, v37
	v_sub_f32_e32 v37, v38, v56
	v_mul_f32_e32 v37, 0x3fb8aa3b, v37
	v_sub_f32_e32 v38, v39, v56
	v_exp_f32_e32 v37, v37
	v_mul_f32_e32 v38, 0x3fb8aa3b, v38
	v_add_f32_e32 v51, v50, v51
	v_exp_f32_e32 v38, v38
	v_add_f32_e32 v39, v36, v51
	v_add_f32_e32 v39, v48, v39
	v_sub_f32_e32 v20, v20, v56
	v_sub_f32_e32 v21, v21, v56
	v_add_f32_e32 v39, v37, v39
	v_mul_f32_e32 v20, 0x3fb8aa3b, v20
	v_mul_f32_e32 v21, 0x3fb8aa3b, v21
	v_add_f32_e32 v39, v38, v39
	v_cvt_pk_f16_f32 v37, v37, v38
	v_exp_f32_e32 v20, v20
	v_exp_f32_e32 v38, v21
	v_sub_f32_e32 v21, v22, v56
	v_sub_f32_e32 v22, v23, v56
	v_mul_f32_e32 v21, 0x3fb8aa3b, v21
	v_mul_f32_e32 v22, 0x3fb8aa3b, v22
	v_exp_f32_e32 v21, v21
	v_exp_f32_e32 v22, v22
	v_add_f32_e32 v23, v20, v39
	v_add_f32_e32 v23, v38, v23
	v_sub_f32_e32 v16, v16, v56
	v_sub_f32_e32 v17, v17, v56
	v_cvt_pk_f16_f32 v36, v36, v48
	v_add_f32_e32 v23, v21, v23
	v_cvt_pk_f16_f32 v21, v21, v22
	v_cvt_pk_f16_f32 v20, v20, v38
	v_mul_f32_e32 v16, 0x3fb8aa3b, v16
	v_mul_f32_e32 v17, 0x3fb8aa3b, v17
	ds_write2_b64 v92, v[36:37], v[20:21] offset0:16 offset1:20
	v_exp_f32_e32 v16, v16
	v_exp_f32_e32 v20, v17
	v_sub_f32_e32 v17, v18, v56
	v_mul_f32_e32 v17, 0x3fb8aa3b, v17
	v_sub_f32_e32 v18, v19, v56
	v_exp_f32_e32 v17, v17
	v_mul_f32_e32 v18, 0x3fb8aa3b, v18
	v_add_f32_e32 v23, v22, v23
	v_exp_f32_e32 v18, v18
	v_add_f32_e32 v19, v16, v23
	v_add_f32_e32 v19, v20, v19
	v_sub_f32_e32 v12, v12, v56
	v_sub_f32_e32 v13, v13, v56
	v_add_f32_e32 v19, v17, v19
	v_mul_f32_e32 v12, 0x3fb8aa3b, v12
	v_mul_f32_e32 v13, 0x3fb8aa3b, v13
	v_add_f32_e32 v19, v18, v19
	v_cvt_pk_f16_f32 v17, v17, v18
	v_exp_f32_e32 v12, v12
	v_exp_f32_e32 v18, v13
	v_sub_f32_e32 v13, v14, v56
	v_sub_f32_e32 v14, v15, v56
	v_mul_f32_e32 v13, 0x3fb8aa3b, v13
	v_mul_f32_e32 v14, 0x3fb8aa3b, v14
	v_exp_f32_e32 v13, v13
	v_exp_f32_e32 v14, v14
	v_add_f32_e32 v15, v12, v19
	v_add_f32_e32 v15, v18, v15
; #define LAS __attribute__((address_space(3)))
; __device__ __forceinline__ void mem_attn_phase(int wv, const Args& A, LAS unsigned char* lds, int G) {
;     ...
;         for (int kt = 0; kt < 16; ++kt) { h16x4 p4;
; #pragma unroll
;             for (int r = 0; r < 4; ++r) { const float p = __expf(lg[kt][r] - m); sm += p; p4[r] = (h16)p; }
;             *(LAS u32x2*)(Pw + fr * 264 + kt * 16 + fq * 4) = __builtin_bit_cast(u32x2, p4); }
;         sm += __shfl_xor(sm, 16); sm += __shfl_xor(sm, 32);
;         const float inv = 1.f / sm;
; #pragma unroll
;         for (int db = 0; db < 8; ++db) { f32x4 o = {0.f, 0.f, 0.f, 0.f};
; #pragma unroll
;             for (int ks = 0; ks < 8; ++ks) { const h16x8 vf = __builtin_bit_cast(h16x8, *(const u32x4*)(VTb + (size_t)(db * 16 + fr) * 256 + ks * 32 + fq * 8));
;                 const h16x8 pf = *(const LAS h16x8*)(Pw + fr * 264 + ks * 32 + fq * 8); o = __builtin_amdgcn_mfma_f32_16x16x32_f16(vf, pf, o, 0, 0, 0); }
	v_cvt_pk_f16_f32 v16, v16, v20
	v_add_f32_e32 v15, v13, v15
	v_cvt_pk_f16_f32 v13, v13, v14
	v_cvt_pk_f16_f32 v12, v12, v18
	ds_write2_b64 v92, v[16:17], v[12:13] offset0:24 offset1:28
	v_sub_f32_e32 v12, v24, v56
	v_sub_f32_e32 v13, v25, v56
	v_mul_f32_e32 v12, 0x3fb8aa3b, v12
	v_mul_f32_e32 v13, 0x3fb8aa3b, v13
	v_add_f32_e32 v15, v14, v15
	v_exp_f32_e32 v12, v12
	v_exp_f32_e32 v14, v13
	v_sub_f32_e32 v13, v26, v56
	v_mul_f32_e32 v13, 0x3fb8aa3b, v13
	v_sub_f32_e32 v16, v27, v56
	v_exp_f32_e32 v13, v13
	v_mul_f32_e32 v16, 0x3fb8aa3b, v16
	v_exp_f32_e32 v16, v16
	v_add_f32_e32 v15, v12, v15
	v_add_f32_e32 v15, v14, v15
	v_add_f32_e32 v15, v13, v15
	v_cvt_pk_f16_f32 v12, v12, v14
	v_sub_f32_e32 v14, v40, v56
	v_add_f32_e32 v15, v16, v15
	v_cvt_pk_f16_f32 v13, v13, v16
	v_mul_f32_e32 v14, 0x3fb8aa3b, v14
	v_sub_f32_e32 v16, v41, v56
	v_exp_f32_e32 v14, v14
	v_mul_f32_e32 v16, 0x3fb8aa3b, v16
	v_sub_f32_e32 v17, v42, v56
	v_exp_f32_e32 v16, v16
	v_mul_f32_e32 v17, 0x3fb8aa3b, v17
	v_sub_f32_e32 v18, v43, v56
	v_exp_f32_e32 v17, v17
	v_mul_f32_e32 v18, 0x3fb8aa3b, v18
	v_exp_f32_e32 v18, v18
	v_add_f32_e32 v15, v14, v15
	v_add_f32_e32 v15, v16, v15
	v_add_f32_e32 v15, v17, v15
	v_add_f32_e32 v19, v18, v15
	v_cvt_pk_f16_f32 v15, v17, v18
	v_cvt_pk_f16_f32 v14, v14, v16
	ds_write2_b64 v92, v[12:13], v[14:15] offset0:32 offset1:36
	v_sub_f32_e32 v12, v44, v56
	v_sub_f32_e32 v13, v45, v56
	v_mul_f32_e32 v12, 0x3fb8aa3b, v12
	v_mul_f32_e32 v13, 0x3fb8aa3b, v13
	v_exp_f32_e32 v12, v12
	v_exp_f32_e32 v13, v13
	v_sub_f32_e32 v14, v46, v56
	v_sub_f32_e32 v15, v47, v56
	v_mul_f32_e32 v14, 0x3fb8aa3b, v14
	v_mul_f32_e32 v15, 0x3fb8aa3b, v15
	v_exp_f32_e32 v14, v14
	v_exp_f32_e32 v15, v15
	v_add_f32_e32 v16, v12, v19
	v_cvt_pk_f16_f32 v36, v12, v13
	v_sub_f32_e32 v12, v32, v56
	v_add_f32_e32 v16, v13, v16
	v_mul_f32_e32 v12, 0x3fb8aa3b, v12
	v_sub_f32_e32 v13, v33, v56
	v_add_f32_e32 v16, v14, v16
	v_cvt_pk_f16_f32 v37, v14, v15
	v_exp_f32_e32 v12, v12
	v_mul_f32_e32 v13, 0x3fb8aa3b, v13
	v_sub_f32_e32 v14, v34, v56
	v_add_f32_e32 v16, v15, v16
	v_exp_f32_e32 v13, v13
	v_mul_f32_e32 v14, 0x3fb8aa3b, v14
	v_sub_f32_e32 v15, v35, v56
	v_sub_f32_e32 v17, v28, v56
	v_exp_f32_e32 v14, v14
	v_mul_f32_e32 v15, 0x3fb8aa3b, v15
	v_mul_f32_e32 v17, 0x3fb8aa3b, v17
	v_exp_f32_e32 v15, v15
	v_exp_f32_e32 v46, v17
	v_sub_f32_e32 v17, v29, v56
	v_add_f32_e32 v16, v12, v16
	v_mul_f32_e32 v17, 0x3fb8aa3b, v17
	v_add_f32_e32 v16, v13, v16
	v_exp_f32_e32 v47, v17
	v_add_f32_e32 v16, v14, v16
	v_add_f32_e32 v16, v15, v16
	v_cvt_pk_f16_f32 v38, v12, v13
	v_add_f32_e32 v12, v46, v16
	v_cvt_pk_f16_f32 v39, v14, v15
	v_add_f32_e32 v14, v47, v12
	v_sub_f32_e32 v12, v30, v56
	v_mul_f32_e32 v12, 0x3fb8aa3b, v12
	v_exp_f32_e32 v48, v12
	v_sub_f32_e32 v12, v31, v56
	v_mul_f32_e32 v15, 0x3fb8aa3b, v12
	v_lshl_add_u64 v[12:13], v[90:91], 0, v[80:81]
	v_lshl_add_u64 v[40:41], v[12:13], 0, v[86:87]
	global_load_dwordx4 v[42:45], v[40:41], off
	global_load_dwordx4 v[20:23], v[40:41], off offset:64
	global_load_dwordx4 v[32:35], v[40:41], off offset:128
	global_load_dwordx4 v[16:19], v[40:41], off offset:192
	global_load_dwordx4 v[28:31], v[40:41], off offset:256
	v_sub_f32_e32 v8, v8, v56
	v_sub_f32_e32 v9, v9, v56
	v_mul_f32_e32 v8, 0x3fb8aa3b, v8
	v_mul_f32_e32 v9, 0x3fb8aa3b, v9
	v_exp_f32_e32 v49, v15
	v_exp_f32_e32 v50, v8
	v_add_f32_e32 v8, v48, v14
	v_exp_f32_e32 v51, v9
	v_sub_f32_e32 v9, v10, v56
	global_load_dwordx4 v[12:15], v[40:41], off offset:320
	v_mul_f32_e32 v9, 0x3fb8aa3b, v9
	v_exp_f32_e32 v52, v9
	v_sub_f32_e32 v9, v11, v56
	v_mul_f32_e32 v9, 0x3fb8aa3b, v9
	v_add_f32_e32 v8, v49, v8
	v_exp_f32_e32 v53, v9
	global_load_dwordx4 v[24:27], v[40:41], off offset:384
	v_add_f32_e32 v8, v50, v8
	v_add_f32_e32 v8, v51, v8
	v_add_f32_e32 v8, v52, v8
	v_add_f32_e32 v54, v53, v8
	global_load_dwordx4 v[8:11], v[40:41], off offset:448
	s_mov_b32 s98, 0x2000
	s_mov_b32 s99, 0
	v_lshl_add_u64 v[234:235], v[40:41], 0, s[98:99]
	global_load_dwordx4 v[182:185], v[234:235], off
	global_load_dwordx4 v[186:189], v[234:235], off offset:64
	global_load_dwordx4 v[190:193], v[234:235], off offset:128
	global_load_dwordx4 v[194:197], v[234:235], off offset:192
	global_load_dwordx4 v[198:201], v[234:235], off offset:256
	global_load_dwordx4 v[202:205], v[234:235], off offset:320
	global_load_dwordx4 v[206:209], v[234:235], off offset:384
	global_load_dwordx4 v[210:213], v[234:235], off offset:448
	v_lshl_add_u64 v[234:235], v[234:235], 0, s[98:99]
	global_load_dwordx4 v[214:217], v[234:235], off
	global_load_dwordx4 v[218:221], v[234:235], off offset:64
	global_load_dwordx4 v[222:225], v[234:235], off offset:128
	global_load_dwordx4 v[226:229], v[234:235], off offset:192
	global_load_dwordx4 v[230:233], v[234:235], off offset:256
	global_load_dwordx4 v[240:243], v[234:235], off offset:320
	global_load_dwordx4 v[244:247], v[234:235], off offset:384
	global_load_dwordx4 v[248:251], v[234:235], off offset:448
	v_sub_f32_e32 v0, v0, v56
	v_mul_f32_e32 v0, 0x3fb8aa3b, v0
	v_exp_f32_e32 v55, v0
	v_sub_f32_e32 v0, v1, v56
	v_mul_f32_e32 v0, 0x3fb8aa3b, v0
	v_exp_f32_e32 v57, v0
	v_sub_f32_e32 v0, v2, v56
	v_sub_f32_e32 v1, v4, v56
	v_mul_f32_e32 v0, 0x3fb8aa3b, v0
	v_mul_f32_e32 v1, 0x3fb8aa3b, v1
	v_exp_f32_e32 v58, v0
	v_sub_f32_e32 v0, v3, v56
	v_exp_f32_e32 v4, v1
	v_sub_f32_e32 v1, v5, v56
	v_mul_f32_e32 v0, 0x3fb8aa3b, v0
	v_mul_f32_e32 v1, 0x3fb8aa3b, v1
	v_exp_f32_e32 v59, v0
	v_exp_f32_e32 v5, v1
	v_sub_f32_e32 v1, v6, v56
	v_add_f32_e32 v0, v55, v54
	v_mul_f32_e32 v1, 0x3fb8aa3b, v1
	v_add_f32_e32 v0, v57, v0
	v_exp_f32_e32 v6, v1
	v_sub_f32_e32 v1, v7, v56
	v_add_f32_e32 v0, v58, v0
	v_mul_f32_e32 v1, 0x3fb8aa3b, v1
	v_add_f32_e32 v0, v59, v0
	v_exp_f32_e32 v7, v1
	v_add_f32_e32 v0, v4, v0
	v_add_f32_e32 v0, v5, v0
	v_add_f32_e32 v0, v6, v0
	v_add_f32_e32 v2, v7, v0
	ds_bpermute_b32 v54, v175, v2
	ds_write2_b64 v92, v[36:37], v[38:39] offset0:40 offset1:44
	v_cvt_pk_f16_f32 v1, v48, v49
	v_cvt_pk_f16_f32 v0, v46, v47
	v_cvt_pk_f16_f32 v3, v52, v53
	s_waitcnt lgkmcnt(1)
; #define LAS __attribute__((address_space(3)))
; __device__ __forceinline__ void mem_attn_phase(int wv, const Args& A, LAS unsigned char* lds, int G) {
;     ...
;         sm += __shfl_xor(sm, 16); sm += __shfl_xor(sm, 32);
;         const float inv = 1.f / sm;
; #pragma unroll
;         for (int db = 0; db < 8; ++db) { f32x4 o = {0.f, 0.f, 0.f, 0.f};
; #pragma unroll
;             for (int ks = 0; ks < 8; ++ks) { const h16x8 vf = __builtin_bit_cast(h16x8, *(const u32x4*)(VTb + (size_t)(db * 16 + fr) * 256 + ks * 32 + fq * 8));
;                 const h16x8 pf = *(const LAS h16x8*)(Pw + fr * 264 + ks * 32 + fq * 8); o = __builtin_amdgcn_mfma_f32_16x16x32_f16(vf, pf, o, 0, 0, 0); }
;             h16x4 o4; o4[0] = (h16)(o[0] * inv); o4[1] = (h16)(o[1] * inv); o4[2] = (h16)(o[2] * inv); o4[3] = (h16)(o[3] * inv);
;             *(u32x2*)(MO + (row0 + fr) * 512 + h * 128 + db * 16 + fq * 4) = __builtin_bit_cast(u32x2, o4); }
	v_add_f32_e32 v36, v2, v54
	ds_bpermute_b32 v37, v176, v36
	v_cvt_pk_f16_f32 v2, v50, v51
	ds_write2_b64 v92, v[0:1], v[2:3] offset0:48 offset1:52
	v_cvt_pk_f16_f32 v1, v58, v59
	v_cvt_pk_f16_f32 v3, v6, v7
	s_waitcnt lgkmcnt(1)
	v_add_f32_e32 v66, v36, v37
	v_div_scale_f32 v58, s[26:27], v66, v66, 1.0
	v_rcp_f32_e32 v59, v58
	v_cvt_pk_f16_f32 v2, v4, v5
	ds_read_b128 v[4:7], v94
	v_cvt_pk_f16_f32 v0, v55, v57
	ds_write2_b64 v92, v[0:1], v[2:3] offset0:56 offset1:60
	v_fma_f32 v0, -v58, v59, 1.0
	v_fmac_f32_e32 v59, v0, v59
	ds_read_b128 v[36:39], v94 offset:64
	ds_read_b128 v[0:3], v94
	s_waitcnt vmcnt(23) lgkmcnt(3)
	v_mfma_f32_16x16x32_f16 v[42:45], v[42:45], v[4:7], 0
	ds_read_b128 v[46:49], v94 offset:128
	ds_read_b128 v[50:53], v94
	v_div_scale_f32 v60, vcc, 1.0, v66, 1.0
	s_waitcnt vmcnt(22) lgkmcnt(3)
	v_mfma_f32_16x16x32_f16 v[20:23], v[20:23], v[36:39], v[42:45]
	s_nop 2
	ds_read_b128 v[42:45], v94 offset:192
	ds_read_b128 v[54:57], v94 offset:128
	v_mul_f32_e32 v61, v60, v59
	v_fma_f32 v62, -v58, v61, v60
	s_waitcnt vmcnt(21) lgkmcnt(3)
	v_mfma_f32_16x16x32_f16 v[20:23], v[32:35], v[46:49], v[20:23]
	ds_read_b128 v[32:35], v94 offset:128
	v_fmac_f32_e32 v61, v62, v59
	v_fma_f32 v58, -v58, v61, v60
	s_waitcnt vmcnt(20) lgkmcnt(2)
	v_mfma_f32_16x16x32_f16 v[16:19], v[16:19], v[42:45], v[20:23]
	v_div_fmas_f32 v67, v58, v59, v61
	s_nop 1
	ds_read_b128 v[20:23], v94 offset:256
	ds_read_b128 v[58:61], v94 offset:320
	ds_read_b128 v[62:65], v94 offset:256
	s_waitcnt vmcnt(19) lgkmcnt(2)
	v_mfma_f32_16x16x32_f16 v[28:31], v[28:31], v[20:23], v[16:19]
	s_nop 2
	v_div_fixup_f32 v16, v67, v66, 1.0
	ds_read_b128 v[66:69], v94 offset:384
	ds_read_b128 v[70:73], v94 offset:256
	v_lshl_add_u64 v[18:19], s[10:11], 0, v[88:89]
	s_waitcnt vmcnt(18) lgkmcnt(3)
	v_mfma_f32_16x16x32_f16 v[12:15], v[12:15], v[58:61], v[28:31]
	s_nop 2
	ds_read_b128 v[28:31], v94 offset:448
	ds_read_b128 v[88:91], v94 offset:384
	ds_read_b128 v[96:99], v94 offset:384
	s_waitcnt vmcnt(17) lgkmcnt(4)
	v_mfma_f32_16x16x32_f16 v[24:27], v[24:27], v[66:69], v[12:15]
	s_waitcnt vmcnt(16) lgkmcnt(2)
	v_mfma_f32_16x16x32_f16 v[8:11], v[8:11], v[28:31], v[24:27]
	s_nop 0
	v_lshl_add_u64 v[12:13], v[18:19], 0, v[78:79]
	v_lshl_add_u64 v[12:13], v[12:13], 0, v[84:85]
	s_nop 4
	v_fma_mixlo_f16 v14, v8, v16, 0
	v_mov_b32_e32 v8, v9
	v_mov_b32_e32 v9, v10
	v_pk_mul_f32 v[8:9], v[8:9], v[16:17] op_sel_hi:[1,0]
	v_fma_mixlo_f16 v10, v11, v16, 0
	v_cvt_pk_f16_f32 v9, v8, v9
	v_pack_b32_f16 v8, v14, v9
	v_alignbit_b32 v9, v10, v9, 16
	v_add_co_u32_e32 v14, vcc, s40, v40
	global_store_dwordx2 v[12:13], v[8:9], off
	v_cmp_lt_i32_e32 vcc, s48, v77
	s_or_b64 s[20:21], vcc, s[20:21]
	ds_read_b128 v[42:45], v94
	ds_read_b128 v[46:49], v94 offset:64
	ds_read_b128 v[50:53], v94 offset:128
	ds_read_b128 v[54:57], v94 offset:192
	ds_read_b128 v[58:61], v94 offset:256
	ds_read_b128 v[62:65], v94 offset:320
	ds_read_b128 v[66:69], v94 offset:384
	ds_read_b128 v[70:73], v94 offset:448
	s_waitcnt lgkmcnt(0)
	s_waitcnt vmcnt(15)
	v_mfma_f32_16x16x32_f16 v[4:7], v[182:185], v[42:45], 0
	v_lshl_add_u64 v[234:235], v[234:235], 0, s[98:99]
	global_load_dwordx4 v[182:185], v[234:235], off
	s_waitcnt vmcnt(15)
	v_mfma_f32_16x16x32_f16 v[4:7], v[186:189], v[46:49], v[4:7]
	global_load_dwordx4 v[186:189], v[234:235], off offset:64
	s_waitcnt vmcnt(15)
	v_mfma_f32_16x16x32_f16 v[4:7], v[190:193], v[50:53], v[4:7]
	global_load_dwordx4 v[190:193], v[234:235], off offset:128
	s_waitcnt vmcnt(15)
	v_mfma_f32_16x16x32_f16 v[4:7], v[194:197], v[54:57], v[4:7]
	global_load_dwordx4 v[194:197], v[234:235], off offset:192
	s_waitcnt vmcnt(15)
	v_mfma_f32_16x16x32_f16 v[4:7], v[198:201], v[58:61], v[4:7]
	global_load_dwordx4 v[198:201], v[234:235], off offset:256
	s_waitcnt vmcnt(15)
	v_mfma_f32_16x16x32_f16 v[4:7], v[202:205], v[62:65], v[4:7]
	global_load_dwordx4 v[202:205], v[234:235], off offset:320
	s_waitcnt vmcnt(15)
	v_mfma_f32_16x16x32_f16 v[4:7], v[206:209], v[66:69], v[4:7]
	global_load_dwordx4 v[206:209], v[234:235], off offset:384
	s_waitcnt vmcnt(15)
	v_mfma_f32_16x16x32_f16 v[4:7], v[210:213], v[70:73], v[4:7]
	global_load_dwordx4 v[210:213], v[234:235], off offset:448
	s_waitcnt vmcnt(15)
	v_mfma_f32_16x16x32_f16 v[0:3], v[214:217], v[42:45], 0
	v_lshl_add_u64 v[234:235], v[234:235], 0, s[98:99]
	global_load_dwordx4 v[214:217], v[234:235], off
	s_waitcnt vmcnt(15)
	v_mfma_f32_16x16x32_f16 v[0:3], v[218:221], v[46:49], v[0:3]
	global_load_dwordx4 v[218:221], v[234:235], off offset:64
	s_waitcnt vmcnt(15)
	v_mfma_f32_16x16x32_f16 v[0:3], v[222:225], v[50:53], v[0:3]
	global_load_dwordx4 v[222:225], v[234:235], off offset:128
	s_waitcnt vmcnt(15)
	v_mfma_f32_16x16x32_f16 v[0:3], v[226:229], v[54:57], v[0:3]
	global_load_dwordx4 v[226:229], v[234:235], off offset:192
	s_waitcnt vmcnt(15)
	v_mul_f32_e32 v4, v4, v16
	v_mul_f32_e32 v5, v5, v16
	v_mul_f32_e32 v6, v6, v16
	v_mul_f32_e32 v7, v7, v16
	v_cvt_pk_f16_f32 v10, v4, v5
	v_cvt_pk_f16_f32 v11, v6, v7
	global_store_dwordx2 v[12:13], v[10:11], off offset:32
	v_mfma_f32_16x16x32_f16 v[0:3], v[230:233], v[58:61], v[0:3]
	global_load_dwordx4 v[230:233], v[234:235], off offset:256
	s_waitcnt vmcnt(15)
	v_mfma_f32_16x16x32_f16 v[0:3], v[240:243], v[62:65], v[0:3]
	global_load_dwordx4 v[240:243], v[234:235], off offset:320
	s_waitcnt vmcnt(15)
	v_mfma_f32_16x16x32_f16 v[0:3], v[244:247], v[66:69], v[0:3]
	global_load_dwordx4 v[244:247], v[234:235], off offset:384
	s_waitcnt vmcnt(15)
	v_mfma_f32_16x16x32_f16 v[0:3], v[248:251], v[70:73], v[0:3]
	global_load_dwordx4 v[248:251], v[234:235], off offset:448
	s_waitcnt vmcnt(15)
; #define LAS __attribute__((address_space(3)))
; __device__ __forceinline__ void mem_attn_phase(int wv, const Args& A, LAS unsigned char* lds, int G) {
;     ...
;         for (int db = 0; db < 8; ++db) { f32x4 o = {0.f, 0.f, 0.f, 0.f};
; #pragma unroll
;             for (int ks = 0; ks < 8; ++ks) { const h16x8 vf = __builtin_bit_cast(h16x8, *(const u32x4*)(VTb + (size_t)(db * 16 + fr) * 256 + ks * 32 + fq * 8));
;                 const h16x8 pf = *(const LAS h16x8*)(Pw + fr * 264 + ks * 32 + fq * 8); o = __builtin_amdgcn_mfma_f32_16x16x32_f16(vf, pf, o, 0, 0, 0); }
;             h16x4 o4; o4[0] = (h16)(o[0] * inv); o4[1] = (h16)(o[1] * inv); o4[2] = (h16)(o[2] * inv); o4[3] = (h16)(o[3] * inv);
;             *(u32x2*)(MO + (row0 + fr) * 512 + h * 128 + db * 16 + fq * 4) = __builtin_bit_cast(u32x2, o4); }
	v_mfma_f32_16x16x32_f16 v[4:7], v[182:185], v[42:45], 0
	v_lshl_add_u64 v[234:235], v[234:235], 0, s[98:99]
	global_load_dwordx4 v[182:185], v[234:235], off
	s_waitcnt vmcnt(15)
	v_mfma_f32_16x16x32_f16 v[4:7], v[186:189], v[46:49], v[4:7]
	global_load_dwordx4 v[186:189], v[234:235], off offset:64
	s_waitcnt vmcnt(15)
	v_mfma_f32_16x16x32_f16 v[4:7], v[190:193], v[50:53], v[4:7]
	global_load_dwordx4 v[190:193], v[234:235], off offset:128
	s_waitcnt vmcnt(15)
	v_mfma_f32_16x16x32_f16 v[4:7], v[194:197], v[54:57], v[4:7]
	global_load_dwordx4 v[194:197], v[234:235], off offset:192
	s_waitcnt vmcnt(15)
	v_mul_f32_e32 v0, v0, v16
	v_mul_f32_e32 v1, v1, v16
	v_mul_f32_e32 v2, v2, v16
	v_mul_f32_e32 v3, v3, v16
	v_cvt_pk_f16_f32 v8, v0, v1
	v_cvt_pk_f16_f32 v9, v2, v3
	global_store_dwordx2 v[12:13], v[8:9], off offset:64
	v_mfma_f32_16x16x32_f16 v[4:7], v[198:201], v[58:61], v[4:7]
	global_load_dwordx4 v[198:201], v[234:235], off offset:256
	s_waitcnt vmcnt(15)
	v_mfma_f32_16x16x32_f16 v[4:7], v[202:205], v[62:65], v[4:7]
	global_load_dwordx4 v[202:205], v[234:235], off offset:320
	s_waitcnt vmcnt(15)
	v_mfma_f32_16x16x32_f16 v[4:7], v[206:209], v[66:69], v[4:7]
	global_load_dwordx4 v[206:209], v[234:235], off offset:384
	s_waitcnt vmcnt(15)
	v_mfma_f32_16x16x32_f16 v[4:7], v[210:213], v[70:73], v[4:7]
	global_load_dwordx4 v[210:213], v[234:235], off offset:448
	s_waitcnt vmcnt(15)
	v_mfma_f32_16x16x32_f16 v[0:3], v[214:217], v[42:45], 0
	v_lshl_add_u64 v[234:235], v[234:235], 0, s[98:99]
	global_load_dwordx4 v[214:217], v[234:235], off
	s_waitcnt vmcnt(15)
	v_mfma_f32_16x16x32_f16 v[0:3], v[218:221], v[46:49], v[0:3]
	global_load_dwordx4 v[218:221], v[234:235], off offset:64
	s_waitcnt vmcnt(15)
	v_mfma_f32_16x16x32_f16 v[0:3], v[222:225], v[50:53], v[0:3]
	global_load_dwordx4 v[222:225], v[234:235], off offset:128
	s_waitcnt vmcnt(15)
	v_mfma_f32_16x16x32_f16 v[0:3], v[226:229], v[54:57], v[0:3]
	global_load_dwordx4 v[226:229], v[234:235], off offset:192
	s_waitcnt vmcnt(15)
	v_mul_f32_e32 v4, v4, v16
	v_mul_f32_e32 v5, v5, v16
	v_mul_f32_e32 v6, v6, v16
	v_mul_f32_e32 v7, v7, v16
	v_cvt_pk_f16_f32 v10, v4, v5
	v_cvt_pk_f16_f32 v11, v6, v7
	global_store_dwordx2 v[12:13], v[10:11], off offset:96
	v_mfma_f32_16x16x32_f16 v[0:3], v[230:233], v[58:61], v[0:3]
	global_load_dwordx4 v[230:233], v[234:235], off offset:256
	s_waitcnt vmcnt(15)
	v_mfma_f32_16x16x32_f16 v[0:3], v[240:243], v[62:65], v[0:3]
	global_load_dwordx4 v[240:243], v[234:235], off offset:320
	s_waitcnt vmcnt(15)
	v_mfma_f32_16x16x32_f16 v[0:3], v[244:247], v[66:69], v[0:3]
	global_load_dwordx4 v[244:247], v[234:235], off offset:384
	s_waitcnt vmcnt(15)
	v_mfma_f32_16x16x32_f16 v[0:3], v[248:251], v[70:73], v[0:3]
	global_load_dwordx4 v[248:251], v[234:235], off offset:448
	s_waitcnt vmcnt(15)
	v_mfma_f32_16x16x32_f16 v[4:7], v[182:185], v[42:45], 0
	v_lshl_add_u64 v[234:235], v[234:235], 0, s[98:99]
	global_load_dwordx4 v[182:185], v[234:235], off
	s_waitcnt vmcnt(15)
	v_mfma_f32_16x16x32_f16 v[4:7], v[186:189], v[46:49], v[4:7]
	global_load_dwordx4 v[186:189], v[234:235], off offset:64
	s_waitcnt vmcnt(15)
	v_mfma_f32_16x16x32_f16 v[4:7], v[190:193], v[50:53], v[4:7]
	global_load_dwordx4 v[190:193], v[234:235], off offset:128
	s_waitcnt vmcnt(15)
	v_mfma_f32_16x16x32_f16 v[4:7], v[194:197], v[54:57], v[4:7]
	global_load_dwordx4 v[194:197], v[234:235], off offset:192
	s_waitcnt vmcnt(15)
	v_mul_f32_e32 v0, v0, v16
	v_mul_f32_e32 v1, v1, v16
	v_mul_f32_e32 v2, v2, v16
	v_mul_f32_e32 v3, v3, v16
	v_cvt_pk_f16_f32 v8, v0, v1
	v_cvt_pk_f16_f32 v9, v2, v3
	global_store_dwordx2 v[12:13], v[8:9], off offset:128
	v_mfma_f32_16x16x32_f16 v[4:7], v[198:201], v[58:61], v[4:7]
	global_load_dwordx4 v[198:201], v[234:235], off offset:256
	s_waitcnt vmcnt(15)
	v_mfma_f32_16x16x32_f16 v[4:7], v[202:205], v[62:65], v[4:7]
	global_load_dwordx4 v[202:205], v[234:235], off offset:320
	s_waitcnt vmcnt(15)
	v_mfma_f32_16x16x32_f16 v[4:7], v[206:209], v[66:69], v[4:7]
	global_load_dwordx4 v[206:209], v[234:235], off offset:384
	s_waitcnt vmcnt(15)
	v_mfma_f32_16x16x32_f16 v[4:7], v[210:213], v[70:73], v[4:7]
	global_load_dwordx4 v[210:213], v[234:235], off offset:448
	s_waitcnt vmcnt(15)
	v_mfma_f32_16x16x32_f16 v[0:3], v[214:217], v[42:45], 0
	s_waitcnt vmcnt(14)
	v_mfma_f32_16x16x32_f16 v[0:3], v[218:221], v[46:49], v[0:3]
	s_waitcnt vmcnt(13)
	v_mfma_f32_16x16x32_f16 v[0:3], v[222:225], v[50:53], v[0:3]
	s_waitcnt vmcnt(12)
	v_mfma_f32_16x16x32_f16 v[0:3], v[226:229], v[54:57], v[0:3]
	s_waitcnt vmcnt(11)
	v_mul_f32_e32 v4, v4, v16
	v_mul_f32_e32 v5, v5, v16
	v_mul_f32_e32 v6, v6, v16
	v_mul_f32_e32 v7, v7, v16
	v_cvt_pk_f16_f32 v10, v4, v5
	v_cvt_pk_f16_f32 v11, v6, v7
	global_store_dwordx2 v[12:13], v[10:11], off offset:160
	v_mfma_f32_16x16x32_f16 v[0:3], v[230:233], v[58:61], v[0:3]
	s_waitcnt vmcnt(10)
	v_mfma_f32_16x16x32_f16 v[0:3], v[240:243], v[62:65], v[0:3]
	s_waitcnt vmcnt(9)
	v_mfma_f32_16x16x32_f16 v[0:3], v[244:247], v[66:69], v[0:3]
	s_waitcnt vmcnt(8)
	v_mfma_f32_16x16x32_f16 v[0:3], v[248:251], v[70:73], v[0:3]
	s_waitcnt vmcnt(7)
	v_mfma_f32_16x16x32_f16 v[4:7], v[182:185], v[42:45], 0
	s_waitcnt vmcnt(6)
	v_mfma_f32_16x16x32_f16 v[4:7], v[186:189], v[46:49], v[4:7]
	s_waitcnt vmcnt(5)
	v_mfma_f32_16x16x32_f16 v[4:7], v[190:193], v[50:53], v[4:7]
	s_waitcnt vmcnt(4)
	v_mfma_f32_16x16x32_f16 v[4:7], v[194:197], v[54:57], v[4:7]
	s_waitcnt vmcnt(3)
	v_mul_f32_e32 v0, v0, v16
	v_mul_f32_e32 v1, v1, v16
	v_mul_f32_e32 v2, v2, v16
	v_mul_f32_e32 v3, v3, v16
	v_cvt_pk_f16_f32 v8, v0, v1
	v_cvt_pk_f16_f32 v9, v2, v3
	global_store_dwordx2 v[12:13], v[8:9], off offset:192
	v_mfma_f32_16x16x32_f16 v[4:7], v[198:201], v[58:61], v[4:7]
	s_waitcnt vmcnt(2)
	v_mfma_f32_16x16x32_f16 v[4:7], v[202:205], v[62:65], v[4:7]
	s_waitcnt vmcnt(1)
	v_mfma_f32_16x16x32_f16 v[4:7], v[206:209], v[66:69], v[4:7]
	s_waitcnt vmcnt(0)
	v_mfma_f32_16x16x32_f16 v[4:7], v[210:213], v[70:73], v[4:7]
	s_nop 7
	s_nop 1
	v_mul_f32_e32 v4, v4, v16
	v_mul_f32_e32 v5, v5, v16
	v_mul_f32_e32 v6, v6, v16
	v_mul_f32_e32 v7, v7, v16
	v_cvt_pk_f16_f32 v10, v4, v5
	v_cvt_pk_f16_f32 v11, v6, v7
	global_store_dwordx2 v[12:13], v[10:11], off offset:224
	s_andn2_b64 exec, exec, s[20:21]
	s_cbranch_execz .LBB0_2406
